# mix2: Q tile register-prefetched a whole chunk ahead like K and V (replaces the output-row prefetch that used the same registers)
# baseline (speedup 1.0000x reference)
; __device__ void mix_sweep(const Params& P, LAS unsigned char* lds, int tok0, int pos0, int seqlen, int hd, int dir, bool state_only, bool final_pass,
;                           f32x4 (&Cacc)[9], float& m_state, float& aseg_sum, float lgam) {
;     ...
;     { const int c = dir ? 7 : 0; const int tok = tok0 + c * 128;
; #pragma unroll
;       for (int which = 1; which < 3; ++which) { const int cb = which == 0 ? qcol : (which == 1 ? kcol : vcolg);
; #pragma unroll
;           for (int it = 0; it < 4; ++it) { const int item = tid + 512 * it, r = item >> 4, ch = item & 15; t[which][it] = *(const u32x4*)(proj + (size_t)(tok + r) * NPROJ + cb + 8 * ch); } } }
;     ...
;         int tl = tid; asm volatile("" : "+v"(tl));
;         if (!state_only) {
; #pragma unroll
;             for (int it = 0; it < 4; ++it) { const int item = tl + 512 * it, r = item >> 4, ch = item & 15; t[0][it] = *(const u32x4*)(proj + (size_t)(tok + r) * NPROJ + qcol + 8 * ch); } }
.LBB0_96:
	s_and_b64 s[14:15], s[8:9], exec
	v_and_b32_e32 v0, 0x78, v0
	s_cselect_b32 s14, 0, 0x380
	v_lshlrev_b32_e32 v0, 1, v0
	s_or_b32 s14, s14, s79
	s_waitcnt lgkmcnt(2)
	v_lshl_add_u64 v[2:3], s[22:23], 0, v[0:1]
	v_ashrrev_i32_e32 v0, 4, v161
	v_add_u32_e32 v40, s14, v0
	v_add_u32_e32 v0, 0x200, v161
	v_ashrrev_i32_e32 v0, 4, v0
	v_add_u32_e32 v42, s14, v0
	v_add_u32_e32 v0, 0x400, v161
	v_ashrrev_i32_e32 v0, 4, v0
	v_add_u32_e32 v50, s14, v0
	v_add_u32_e32 v0, 0x600, v161
	v_ashrrev_i32_e32 v0, 4, v0
	v_add_u32_e32 v52, s14, v0
	v_ashrrev_i32_e32 v41, 31, v40
	s_lshl_b32 s38, s80, 1
	v_ashrrev_i32_e32 v43, 31, v42
	v_ashrrev_i32_e32 v51, 31, v50
	v_ashrrev_i32_e32 v53, 31, v52
	s_lshl_b32 s14, s81, 1
	s_mov_b32 s15, s39
	v_lshlrev_b64 v[56:57], 13, v[40:41]
	v_lshl_add_u64 v[48:49], v[2:3], 0, s[38:39]
	v_lshlrev_b64 v[58:59], 13, v[42:43]
	v_lshlrev_b64 v[64:65], 13, v[50:51]
	v_lshlrev_b64 v[66:67], 13, v[52:53]
	v_lshl_add_u64 v[2:3], v[2:3], 0, s[14:15]
	v_lshl_add_u64 v[40:41], v[48:49], 0, v[56:57]
	v_lshl_add_u64 v[44:45], v[48:49], 0, v[58:59]
	v_lshl_add_u64 v[50:51], v[48:49], 0, v[64:65]
	v_lshl_add_u64 v[52:53], v[48:49], 0, v[66:67]
	v_lshl_add_u64 v[56:57], v[2:3], 0, v[56:57]
	v_lshl_add_u64 v[60:61], v[2:3], 0, v[58:59]
	v_lshl_add_u64 v[64:65], v[2:3], 0, v[64:65]
	global_load_dwordx4 v[40:43], v[40:41], off
	s_nop 0
	global_load_dwordx4 v[44:47], v[44:45], off
	s_nop 0
	global_load_dwordx4 v[48:51], v[50:51], off
	s_nop 0
	global_load_dwordx4 v[52:55], v[52:53], off
	s_nop 0
	global_load_dwordx4 v[56:59], v[56:57], off
	s_nop 0
	global_load_dwordx4 v[60:63], v[60:61], off
	v_lshl_add_u64 v[2:3], v[2:3], 0, v[66:67]
	global_load_dwordx4 v[64:67], v[64:65], off
	s_nop 0
	global_load_dwordx4 v[68:71], v[2:3], off
	v_lshlrev_b32_e32 v79, 2, v161
	s_add_i32 s15, 0, 0x22000
	v_add_u32_e32 v182, s15, v79
	s_add_i32 s15, 0, 0x22200
	v_lshlrev_b32_e32 v0, 4, v73
	v_add_u32_e32 v183, s15, v79
	v_add_u32_e32 v190, s15, v0
	v_readlane_b32 s15, v253, 49
	s_add_i32 s19, 0, 0x22400
	v_add_u32_e32 v184, s19, v79
	v_add_u32_e32 v194, s15, v75
	s_add_i32 s15, 0, 0x1a000
	v_add_u32_e32 v195, s15, v75
	v_readlane_b32 s15, v253, 50
	s_add_i32 s19, 0, 0x22600
	s_add_i32 s46, 0, 0x22800
	v_add_u32_e32 v196, s15, v75
	s_add_i32 s15, 0, 0x1c000
	v_add_u32_e32 v197, s15, v75
	v_readlane_b32 s15, v253, 51
	v_lshlrev_b32_e32 v189, 2, v73
	v_mov_b32_e32 v73, v1
	v_add_u32_e32 v198, s15, v75
	s_add_i32 s15, 0, 0x1e000
	v_add_u32_e32 v199, s15, v75
	v_readlane_b32 s15, v253, 52
	s_add_i32 s85, 0, 0x10000
	s_mov_b32 s7, 0
	v_add_u32_e32 v200, s15, v75
	v_readlane_b32 s15, v253, 53
	s_mov_b32 s83, 1
	v_add_u32_e32 v185, s19, v79
	v_add_u32_e32 v247, s15, v75
	s_add_i32 s15, 0, 0x12000
	v_add_u32_e32 v248, s15, v75
	v_readlane_b32 s15, v253, 54
	v_add_u32_e32 v187, s46, v79
	v_cmp_eq_u32_e64 s[46:47], 0, v161
	v_add_u32_e32 v249, s15, v75
	s_add_i32 s15, 0, 0x14000
	v_add_u32_e32 v250, s15, v75
	v_readlane_b32 s15, v253, 55
	v_lshl_or_b32 v219, s16, 4, v169
	s_add_i32 s84, s17, 0
	v_add_u32_e32 v251, s15, v75
	s_add_i32 s15, 0, 0x16000
	v_add_u32_e32 v252, s15, v75
	v_readlane_b32 s15, v253, 56
	v_add_u32_e32 v191, 0, v78
	v_lshl_add_u32 v192, v72, 2, s19
	v_lshl_add_u64 v[2:3], s[2:3], 0, v[72:73]
	v_lshl_add_u64 v[152:153], s[4:5], 0, v[72:73]
	v_lshl_add_u64 v[154:155], s[94:95], 0, v[0:1]
	v_add_u32_e32 v193, s18, v75
	v_or_b32_e32 v201, 2, v189
	v_or_b32_e32 v202, 3, v189
	v_or_b32_e32 v204, 16, v189
	v_or_b32_e32 v205, 17, v189
	v_or_b32_e32 v206, 18, v189
	v_or_b32_e32 v207, 19, v189
	v_or_b32_e32 v222, 32, v189
	v_or_b32_e32 v223, 33, v189
	v_or_b32_e32 v224, 34, v189
	v_or_b32_e32 v225, 35, v189
	v_or_b32_e32 v226, 48, v189
	v_or_b32_e32 v227, 49, v189
	v_or_b32_e32 v228, 50, v189
	v_or_b32_e32 v229, 51, v189
	v_or_b32_e32 v230, 64, v189
	v_or_b32_e32 v231, 0x41, v189
	v_or_b32_e32 v232, 0x42, v189
	v_or_b32_e32 v233, 0x43, v189
	v_or_b32_e32 v234, 0x50, v189
	v_or_b32_e32 v235, 0x51, v189
	v_or_b32_e32 v236, 0x52, v189
	v_or_b32_e32 v237, 0x53, v189
	v_or_b32_e32 v238, 0x60, v189
	v_or_b32_e32 v239, 0x61, v189
	v_or_b32_e32 v240, 0x62, v189
	v_or_b32_e32 v241, 0x63, v189
	v_or_b32_e32 v242, 0x70, v189
	v_or_b32_e32 v243, 0x71, v189
	v_or_b32_e32 v244, 0x72, v189
	v_or_b32_e32 v245, 0x73, v189
	v_add_u32_e32 v246, s85, v75
	v_add_u32_e32 v211, s15, v75
	v_add_u32_e32 v164, 0, v79
	s_mov_b32 s86, 6
	s_movk_i32 s87, 0xd000
	v_add_u32_e32 v165, 0, v76
	v_add_u32_e32 v166, 0, v77
	v_add_u32_e32 v167, 0, v74
	v_readlane_b32 s88, v253, 57
	v_lshrrev_b32_e32 v80, 6, v161
	v_lshlrev_b32_e32 v80, 6, v80
	v_mov_b32_e32 v81, 0
	v_lshl_add_u64 v[82:83], v[154:155], 0, v[80:81]
	global_load_dwordx4 v[84:87], v[82:83], off
	v_bfe_u32 v81, v161, 4, 2
	v_lshl_add_u32 v80, v81, 4, v80
	v_add_u32_e32 v80, 0x25a80, v80
	s_waitcnt vmcnt(0)
	ds_write_b128 v80, v[84:87]
	s_xor_b32 s15, s7, 0x380
	s_and_b64 s[16:17], s[8:9], exec
	s_cselect_b32 s15, s7, s15
	s_add_i32 s15, s15, s79
	v_lshlrev_b32_e32 v92, 3, v161
	v_and_b32_e32 v92, 0x78, v92
	v_lshlrev_b32_e32 v92, 1, v92
	v_mov_b32_e32 v93, 0
	v_lshl_add_u64 v[94:95], s[36:37], 0, v[92:93]
	v_ashrrev_i32_e32 v96, 4, v161
	v_add_u32_e32 v96, s15, v96
	v_ashrrev_i32_e32 v97, 31, v96
	v_lshlrev_b64 v[96:97], 13, v[96:97]
	v_lshl_add_u64 v[96:97], v[94:95], 0, v[96:97]
	global_load_dwordx4 v[222:225], v[96:97], off
	v_add_u32_e32 v98, 0x200, v161
	v_ashrrev_i32_e32 v98, 4, v98
	v_add_u32_e32 v98, s15, v98
	v_ashrrev_i32_e32 v99, 31, v98
	v_lshlrev_b64 v[98:99], 13, v[98:99]
	v_lshl_add_u64 v[98:99], v[94:95], 0, v[98:99]
	global_load_dwordx4 v[226:229], v[98:99], off
	v_add_u32_e32 v96, 0x400, v161
	v_ashrrev_i32_e32 v96, 4, v96
	v_add_u32_e32 v96, s15, v96
	v_ashrrev_i32_e32 v97, 31, v96
	v_lshlrev_b64 v[96:97], 13, v[96:97]
	v_lshl_add_u64 v[96:97], v[94:95], 0, v[96:97]
	global_load_dwordx4 v[230:233], v[96:97], off
	v_add_u32_e32 v98, 0x600, v161
	v_ashrrev_i32_e32 v98, 4, v98
	v_add_u32_e32 v98, s15, v98
	v_ashrrev_i32_e32 v99, 31, v98
	v_lshlrev_b64 v[98:99], 13, v[98:99]
	v_lshl_add_u64 v[98:99], v[94:95], 0, v[98:99]
	global_load_dwordx4 v[234:237], v[98:99], off
	s_branch .LBB0_98

; #define LAS __attribute__((address_space(3)))
; __device__ void mix_sweep(const Params& P, LAS unsigned char* lds, int tok0, int pos0, int seqlen, int hd, int dir, bool state_only, bool final_pass,
;                           f32x4 (&Cacc)[9], float& m_state, float& aseg_sum, float lgam) {
;     ...
;         int tl = tid; asm volatile("" : "+v"(tl));
;         if (!state_only) {
; #pragma unroll
;             for (int it = 0; it < 4; ++it) { const int item = tl + 512 * it, r = item >> 4, ch = item & 15; t[0][it] = *(const u32x4*)(proj + (size_t)(tok + r) * NPROJ + qcol + 8 * ch); } }
; #pragma unroll
;     ...
; #pragma unroll
;             for (int it = 0; it < 4; ++it) { const int item = tl + 512 * it, r = item >> 4, ch = item & 15; *(LAS u32x4*)(img + offb(r, ch)) = t[which][it]; } }
;         if (ci < 7) { const int cn = dir ? 6 - ci : ci + 1; const int tokn = tok0 + cn * 128;
; #pragma unroll
;             for (int which = 1; which < 3; ++which) { const int cb = which == 1 ? kcol : vcolg;
; #pragma unroll
;                 for (int it = 0; it < 4; ++it) { const int item = tl + 512 * it, r = item >> 4, ch = item & 15; t[which][it] = *(const u32x4*)(proj + (size_t)(tokn + r) * NPROJ + cb + 8 * ch); } } }
.LBB0_98:
	s_xor_b32 s15, s7, 0x380
	s_and_b64 s[16:17], s[8:9], exec
	s_cselect_b32 s89, s7, s15
	v_mov_b32_e32 v92, v161
	s_add_i32 s89, s89, s79
	s_waitcnt lgkmcnt(0)
	s_barrier
	s_cmpk_eq_i32 s87, 0xfa00
	v_lshlrev_b32_e32 v0, 3, v92
	v_ashrrev_i32_e32 v72, 4, v92
	v_and_b32_e32 v0, 0x78, v0
	v_lshlrev_b32_e32 v0, 1, v0
	v_add_u32_e32 v73, 0x200, v92
	v_ashrrev_i32_e32 v73, 4, v73
	v_add_u32_e32 v74, 0x400, v92
	v_ashrrev_i32_e32 v74, 4, v74
	v_add_u32_e32 v75, 0x600, v92
	v_ashrrev_i32_e32 v75, 4, v75
	v_lshlrev_b32_e32 v94, 2, v72
	v_and_b32_e32 v92, 15, v92
	v_and_b32_e32 v94, 12, v94
	v_bfe_u32 v95, v72, 2, 2
	v_bitop3_b32 v94, v94, v92, v95 bitop3:0x36
	v_lshlrev_b32_e32 v96, 2, v73
	v_lshlrev_b32_e32 v93, 8, v72
	v_lshlrev_b32_e32 v94, 4, v94
	v_and_b32_e32 v96, 12, v96
	v_bfe_u32 v97, v73, 2, 2
	v_add3_u32 v95, s85, v94, v93
	v_bitop3_b32 v96, v96, v92, v97 bitop3:0x36
	v_lshlrev_b32_e32 v98, 2, v74
	s_waitcnt vmcnt(7)
	ds_write_b128 v95, v[56:59]
	v_lshlrev_b32_e32 v95, 8, v73
	v_lshlrev_b32_e32 v96, 4, v96
	v_and_b32_e32 v98, 12, v98
	v_bfe_u32 v99, v74, 2, 2
	v_add3_u32 v97, s85, v96, v95
	v_bitop3_b32 v98, v98, v92, v99 bitop3:0x36
	v_lshlrev_b32_e32 v100, 2, v75
	s_waitcnt vmcnt(6)
	ds_write_b128 v97, v[60:63]
	v_lshlrev_b32_e32 v97, 8, v74
	v_lshlrev_b32_e32 v98, 4, v98
	v_and_b32_e32 v100, 12, v100
	v_bfe_u32 v101, v75, 2, 2
	v_add3_u32 v99, s85, v98, v97
	v_bitop3_b32 v92, v100, v92, v101 bitop3:0x36
	s_waitcnt vmcnt(5)
	ds_write_b128 v99, v[64:67]
	v_lshlrev_b32_e32 v99, 8, v75
	v_lshlrev_b32_e32 v92, 4, v92
	v_add3_u32 v100, s85, v92, v99
	v_add3_u32 v93, 0, v94, v93
	v_add3_u32 v94, 0, v96, v95
	v_add3_u32 v95, 0, v98, v97
	v_add3_u32 v92, 0, v92, v99
	s_waitcnt vmcnt(4)
	ds_write_b128 v100, v[68:71]
	ds_write_b128 v93, v[40:43] offset:32768
	ds_write_b128 v94, v[44:47] offset:32768
	ds_write_b128 v95, v[48:51] offset:32768
	ds_write_b128 v92, v[52:55] offset:32768
	s_waitcnt vmcnt(3)
	ds_write_b128 v93, v[222:225]
	s_waitcnt vmcnt(2)
	ds_write_b128 v94, v[226:229]
	s_waitcnt vmcnt(1)
	ds_write_b128 v95, v[230:233]
	s_waitcnt vmcnt(0)
	ds_write_b128 v92, v[234:237]
	s_cbranch_scc1 .LBB0_100
	s_and_b64 s[16:17], s[8:9], exec
	s_cselect_b32 s15, s83, s86
	s_lshl_b32 s15, s15, 7
	s_add_i32 s15, s15, s79
	v_add_u32_e32 v40, s15, v72
	v_add_u32_e32 v42, s15, v73
	v_add_u32_e32 v50, s15, v74
	v_add_u32_e32 v52, s15, v75
	v_lshl_add_u64 v[56:57], s[22:23], 0, v[0:1]
	v_ashrrev_i32_e32 v41, 31, v40
	v_ashrrev_i32_e32 v43, 31, v42
	v_ashrrev_i32_e32 v51, 31, v50
	v_ashrrev_i32_e32 v53, 31, v52
	s_mov_b32 s15, s39
	v_lshlrev_b64 v[58:59], 13, v[40:41]
	v_lshl_add_u64 v[48:49], v[56:57], 0, s[38:39]
	v_lshlrev_b64 v[60:61], 13, v[42:43]
	v_lshlrev_b64 v[64:65], 13, v[50:51]
	v_lshlrev_b64 v[66:67], 13, v[52:53]
	v_lshl_add_u64 v[76:77], s[36:37], 0, v[0:1]
	v_lshl_add_u64 v[78:79], v[76:77], 0, v[58:59]
	v_lshl_add_u64 v[80:81], v[76:77], 0, v[60:61]
	v_lshl_add_u64 v[82:83], v[76:77], 0, v[64:65]
	v_lshl_add_u64 v[84:85], v[76:77], 0, v[66:67]
	v_lshl_add_u64 v[68:69], v[56:57], 0, s[14:15]
	v_lshl_add_u64 v[40:41], v[48:49], 0, v[58:59]
	v_lshl_add_u64 v[44:45], v[48:49], 0, v[60:61]
	v_lshl_add_u64 v[50:51], v[48:49], 0, v[64:65]
	v_lshl_add_u64 v[52:53], v[48:49], 0, v[66:67]
	v_lshl_add_u64 v[56:57], v[68:69], 0, v[58:59]
	v_lshl_add_u64 v[60:61], v[68:69], 0, v[60:61]
	v_lshl_add_u64 v[64:65], v[68:69], 0, v[64:65]
	v_lshl_add_u64 v[68:69], v[68:69], 0, v[66:67]
	global_load_dwordx4 v[40:43], v[40:41], off
	s_nop 0
	global_load_dwordx4 v[44:47], v[44:45], off
	s_nop 0
	global_load_dwordx4 v[48:51], v[50:51], off
	s_nop 0
	global_load_dwordx4 v[52:55], v[52:53], off
	s_nop 0
	global_load_dwordx4 v[56:59], v[56:57], off
	s_nop 0
	global_load_dwordx4 v[60:63], v[60:61], off
	s_nop 0
	global_load_dwordx4 v[64:67], v[64:65], off
	s_nop 0
	global_load_dwordx4 v[68:71], v[68:69], off
	global_load_dwordx4 v[222:225], v[78:79], off
	global_load_dwordx4 v[226:229], v[80:81], off
	global_load_dwordx4 v[230:233], v[82:83], off
	global_load_dwordx4 v[234:237], v[84:85], off
